# v36 + fused-epilogue residual stage: drop the per-step vmcnt(0) that serialised 15 x_new store round trips per unit (wait kept only on the f32-residual path)
# speedup vs baseline: 1.0005x; 1.0001x over previous
.LBB0_450:
	v_lshlrev_b32_e32 v210, 16, v202
	v_and_b32_e32 v211, 0xffff0000, v202
	v_lshlrev_b32_e32 v212, 16, v203
	v_and_b32_e32 v213, 0xffff0000, v203
	v_lshlrev_b32_e32 v206, 16, v204
	v_and_b32_e32 v207, 0xffff0000, v204
	v_lshlrev_b32_e32 v208, 16, v205
	v_and_b32_e32 v209, 0xffff0000, v205
.LBB0_451:
	v_mov_b32_e32 v231, v230
	v_pk_mul_f32 v[48:49], v[48:49], v[140:141]
	v_pk_mul_f32 v[46:47], v[46:47], v[138:139]
	v_mov_b32_e32 v202, v230
	v_mov_b32_e32 v203, v230
	v_pk_mul_f32 v[40:41], v[40:41], v[136:137]
	v_pk_mul_f32 v[38:39], v[38:39], v[134:135]
	v_pk_fma_f32 v[48:49], v[48:49], v[202:203], v[212:213]
	v_pk_fma_f32 v[46:47], v[46:47], v[230:231], v[210:211]
	v_pk_fma_f32 v[40:41], v[40:41], v[202:203], v[208:209]
	v_pk_fma_f32 v[38:39], v[38:39], v[230:231], v[206:207]
	v_cndmask_b32_e64 v202, 0, 1, s[88:89]
	v_cndmask_b32_e64 v41, v41, v245, s[16:17]
	v_cndmask_b32_e64 v40, v40, v245, s[16:17]
	v_cndmask_b32_e64 v39, v39, v245, s[16:17]
	v_cndmask_b32_e64 v38, v38, v245, s[16:17]
	v_cndmask_b32_e64 v49, v49, v245, s[16:17]
	v_cndmask_b32_e64 v48, v48, v245, s[16:17]
	v_cndmask_b32_e64 v47, v47, v245, s[16:17]
	v_cmp_ne_u32_e64 s[20:21], 1, v202
	s_andn2_b64 vcc, exec, s[88:89]
	v_cndmask_b32_e64 v46, v46, v245, s[16:17]
	s_cbranch_vccnz .LBB0_583
	global_store_dwordx4 v[216:217], v[46:49], off offset:512
	global_store_dwordx4 v[216:217], v[38:41], off offset:528
	s_cbranch_execnz .LBB0_454

.LBB0_454:
	ds_read_b32 v212, v234 offset:8320
	s_nop 0
	v_add3_u32 v202, s36, v218, 16
	v_ashrrev_i32_e32 v203, 31, v202
	v_lshlrev_b64 v[210:211], 11, v[202:203]
	v_or_b32_e32 v210, v210, v239
	s_mov_b64 s[66:67], -1
	s_and_b64 vcc, exec, s[18:19]
	v_lshl_add_u64 v[214:215], v[210:211], 2, s[22:23]
	s_cbranch_vccnz .LBB0_456
	global_load_dwordx4 v[202:205], v[214:215], off offset:16
	global_load_dwordx4 v[206:209], v[214:215], off
	s_waitcnt vmcnt(0)
	s_mov_b64 s[66:67], 0
.LBB0_456:
	s_andn2_b64 vcc, exec, s[66:67]
	s_cbranch_vccnz .LBB0_458
	v_lshlrev_b32_e32 v206, 16, v198
	v_and_b32_e32 v207, 0xffff0000, v198
	v_lshlrev_b32_e32 v208, 16, v199
	v_and_b32_e32 v209, 0xffff0000, v199
	v_lshlrev_b32_e32 v202, 16, v200
	v_and_b32_e32 v203, 0xffff0000, v200
	v_lshlrev_b32_e32 v204, 16, v201
	v_and_b32_e32 v205, 0xffff0000, v201
.LBB0_458:
	v_pk_mul_f32 v[44:45], v[44:45], v[152:153]
	v_pk_mul_f32 v[42:43], v[42:43], v[150:151]
	v_pk_mul_f32 v[36:37], v[36:37], v[148:149]
	v_pk_mul_f32 v[34:35], v[34:35], v[146:147]
	s_waitcnt lgkmcnt(0)
	v_pk_fma_f32 v[44:45], v[44:45], v[212:213], v[208:209] op_sel_hi:[1,0,1]
	v_pk_fma_f32 v[42:43], v[42:43], v[212:213], v[206:207] op_sel_hi:[1,0,1]
	v_pk_fma_f32 v[36:37], v[36:37], v[212:213], v[204:205] op_sel_hi:[1,0,1]
	v_pk_fma_f32 v[34:35], v[34:35], v[212:213], v[202:203] op_sel_hi:[1,0,1]
	v_cndmask_b32_e64 v37, v37, v245, s[16:17]
	v_cndmask_b32_e64 v35, v35, v245, s[16:17]
	v_cndmask_b32_e64 v34, v34, v245, s[16:17]
	v_cndmask_b32_e64 v36, v36, v245, s[16:17]
	v_cndmask_b32_e64 v43, v43, v245, s[16:17]
	v_cndmask_b32_e64 v42, v42, v245, s[16:17]
	v_cndmask_b32_e64 v45, v45, v245, s[16:17]
	v_cndmask_b32_e64 v44, v44, v245, s[16:17]
	s_and_b64 vcc, exec, s[20:21]
	v_lshl_add_u64 v[208:209], v[210:211], 2, s[60:61]
	s_cbranch_vccnz .LBB0_584
	global_store_dwordx4 v[208:209], v[42:45], off
	global_store_dwordx4 v[208:209], v[34:37], off offset:16
	v_lshl_add_u64 v[206:207], v[210:211], 1, s[78:79]
	s_cbranch_execnz .LBB0_461

.LBB0_463:
	v_lshlrev_b32_e32 v202, 16, v194
	v_and_b32_e32 v203, 0xffff0000, v194
	v_lshlrev_b32_e32 v204, 16, v195
	v_and_b32_e32 v205, 0xffff0000, v195
	v_lshlrev_b32_e32 v198, 16, v196
	v_and_b32_e32 v199, 0xffff0000, v196
	v_lshlrev_b32_e32 v200, 16, v197
	v_and_b32_e32 v201, 0xffff0000, v197
.LBB0_464:
	v_mov_b32_e32 v213, v212
	v_pk_mul_f32 v[64:65], v[64:65], v[140:141]
	v_pk_mul_f32 v[62:63], v[62:63], v[138:139]
	v_mov_b32_e32 v194, v212
	v_mov_b32_e32 v195, v212
	v_pk_mul_f32 v[60:61], v[60:61], v[136:137]
	v_pk_mul_f32 v[58:59], v[58:59], v[134:135]
	v_pk_fma_f32 v[64:65], v[64:65], v[194:195], v[204:205]
	v_pk_fma_f32 v[62:63], v[62:63], v[212:213], v[202:203]
	v_pk_fma_f32 v[60:61], v[60:61], v[194:195], v[200:201]
	v_pk_fma_f32 v[58:59], v[58:59], v[212:213], v[198:199]
	v_cndmask_b32_e64 v61, v61, v245, s[16:17]
	v_cndmask_b32_e64 v60, v60, v245, s[16:17]
	v_cndmask_b32_e64 v59, v59, v245, s[16:17]
	v_cndmask_b32_e64 v58, v58, v245, s[16:17]
	v_cndmask_b32_e64 v65, v65, v245, s[16:17]
	v_cndmask_b32_e64 v64, v64, v245, s[16:17]
	v_cndmask_b32_e64 v63, v63, v245, s[16:17]
	s_and_b64 vcc, exec, s[20:21]
	v_cndmask_b32_e64 v62, v62, v245, s[16:17]
	s_cbranch_vccnz .LBB0_585
	global_store_dwordx4 v[208:209], v[62:65], off offset:512
	global_store_dwordx4 v[208:209], v[58:61], off offset:528
	s_cbranch_execnz .LBB0_467

.LBB0_467:
	ds_read_b32 v204, v234 offset:8448
	s_nop 0
	v_add3_u32 v194, s36, v218, 32
	v_ashrrev_i32_e32 v195, 31, v194
	v_lshlrev_b64 v[202:203], 11, v[194:195]
	v_or_b32_e32 v202, v202, v239
	s_mov_b64 s[66:67], -1
	s_and_b64 vcc, exec, s[18:19]
	v_lshl_add_u64 v[206:207], v[202:203], 2, s[22:23]
	s_cbranch_vccnz .LBB0_469
	global_load_dwordx4 v[194:197], v[206:207], off offset:16
	global_load_dwordx4 v[198:201], v[206:207], off
	s_waitcnt vmcnt(0)
	s_mov_b64 s[66:67], 0
.LBB0_469:
	s_andn2_b64 vcc, exec, s[66:67]
	s_cbranch_vccnz .LBB0_471
	v_lshlrev_b32_e32 v198, 16, v190
	v_and_b32_e32 v199, 0xffff0000, v190
	v_lshlrev_b32_e32 v200, 16, v191
	v_and_b32_e32 v201, 0xffff0000, v191
	v_lshlrev_b32_e32 v194, 16, v192
	v_and_b32_e32 v195, 0xffff0000, v192
	v_lshlrev_b32_e32 v196, 16, v193
	v_and_b32_e32 v197, 0xffff0000, v193
.LBB0_471:
	v_pk_mul_f32 v[56:57], v[56:57], v[152:153]
	v_pk_mul_f32 v[54:55], v[54:55], v[150:151]
	v_pk_mul_f32 v[52:53], v[52:53], v[148:149]
	v_pk_mul_f32 v[50:51], v[50:51], v[146:147]
	s_waitcnt lgkmcnt(0)
	v_pk_fma_f32 v[56:57], v[56:57], v[204:205], v[200:201] op_sel_hi:[1,0,1]
	v_pk_fma_f32 v[54:55], v[54:55], v[204:205], v[198:199] op_sel_hi:[1,0,1]
	v_pk_fma_f32 v[52:53], v[52:53], v[204:205], v[196:197] op_sel_hi:[1,0,1]
	v_pk_fma_f32 v[50:51], v[50:51], v[204:205], v[194:195] op_sel_hi:[1,0,1]
	v_cndmask_b32_e64 v53, v53, v245, s[16:17]
	v_cndmask_b32_e64 v51, v51, v245, s[16:17]
	v_cndmask_b32_e64 v50, v50, v245, s[16:17]
	v_cndmask_b32_e64 v52, v52, v245, s[16:17]
	v_cndmask_b32_e64 v55, v55, v245, s[16:17]
	v_cndmask_b32_e64 v54, v54, v245, s[16:17]
	v_cndmask_b32_e64 v57, v57, v245, s[16:17]
	v_cndmask_b32_e64 v56, v56, v245, s[16:17]
	s_and_b64 vcc, exec, s[20:21]
	v_lshl_add_u64 v[200:201], v[202:203], 2, s[60:61]
	s_cbranch_vccnz .LBB0_586
	global_store_dwordx4 v[200:201], v[54:57], off
	global_store_dwordx4 v[200:201], v[50:53], off offset:16
	v_lshl_add_u64 v[198:199], v[202:203], 1, s[78:79]
	s_cbranch_execnz .LBB0_474

.LBB0_476:
	v_lshlrev_b32_e32 v194, 16, v186
	v_and_b32_e32 v195, 0xffff0000, v186
	v_lshlrev_b32_e32 v196, 16, v187
	v_and_b32_e32 v197, 0xffff0000, v187
	v_lshlrev_b32_e32 v190, 16, v188
	v_and_b32_e32 v191, 0xffff0000, v188
	v_lshlrev_b32_e32 v192, 16, v189
	v_and_b32_e32 v193, 0xffff0000, v189
.LBB0_477:
	v_mov_b32_e32 v205, v204
	v_pk_mul_f32 v[88:89], v[88:89], v[140:141]
	v_pk_mul_f32 v[86:87], v[86:87], v[138:139]
	v_mov_b32_e32 v186, v204
	v_mov_b32_e32 v187, v204
	v_pk_mul_f32 v[84:85], v[84:85], v[136:137]
	v_pk_mul_f32 v[82:83], v[82:83], v[134:135]
	v_pk_fma_f32 v[88:89], v[88:89], v[186:187], v[196:197]
	v_pk_fma_f32 v[86:87], v[86:87], v[204:205], v[194:195]
	v_pk_fma_f32 v[84:85], v[84:85], v[186:187], v[192:193]
	v_pk_fma_f32 v[82:83], v[82:83], v[204:205], v[190:191]
	v_cndmask_b32_e64 v85, v85, v245, s[16:17]
	v_cndmask_b32_e64 v84, v84, v245, s[16:17]
	v_cndmask_b32_e64 v83, v83, v245, s[16:17]
	v_cndmask_b32_e64 v82, v82, v245, s[16:17]
	v_cndmask_b32_e64 v89, v89, v245, s[16:17]
	v_cndmask_b32_e64 v88, v88, v245, s[16:17]
	v_cndmask_b32_e64 v87, v87, v245, s[16:17]
	s_and_b64 vcc, exec, s[20:21]
	v_cndmask_b32_e64 v86, v86, v245, s[16:17]
	s_cbranch_vccnz .LBB0_587
	global_store_dwordx4 v[200:201], v[86:89], off offset:512
	global_store_dwordx4 v[200:201], v[82:85], off offset:528
	s_cbranch_execnz .LBB0_480

.LBB0_480:
	ds_read_b32 v196, v234 offset:8576
	s_nop 0
	v_add3_u32 v186, s36, v218, 48
	v_ashrrev_i32_e32 v187, 31, v186
	v_lshlrev_b64 v[194:195], 11, v[186:187]
	v_or_b32_e32 v194, v194, v239
	s_mov_b64 s[66:67], -1
	s_and_b64 vcc, exec, s[18:19]
	v_lshl_add_u64 v[198:199], v[194:195], 2, s[22:23]
	s_cbranch_vccnz .LBB0_482
	global_load_dwordx4 v[186:189], v[198:199], off offset:16
	global_load_dwordx4 v[190:193], v[198:199], off
	s_waitcnt vmcnt(0)
	s_mov_b64 s[66:67], 0
.LBB0_482:
	s_andn2_b64 vcc, exec, s[66:67]
	s_cbranch_vccnz .LBB0_484
	v_lshlrev_b32_e32 v190, 16, v182
	v_and_b32_e32 v191, 0xffff0000, v182
	v_lshlrev_b32_e32 v192, 16, v183
	v_and_b32_e32 v193, 0xffff0000, v183
	v_lshlrev_b32_e32 v186, 16, v184
	v_and_b32_e32 v187, 0xffff0000, v184
	v_lshlrev_b32_e32 v188, 16, v185
	v_and_b32_e32 v189, 0xffff0000, v185
.LBB0_484:
	v_pk_mul_f32 v[80:81], v[80:81], v[152:153]
	v_pk_mul_f32 v[78:79], v[78:79], v[150:151]
	v_pk_mul_f32 v[72:73], v[72:73], v[148:149]
	v_pk_mul_f32 v[70:71], v[70:71], v[146:147]
	s_waitcnt lgkmcnt(0)
	v_pk_fma_f32 v[80:81], v[80:81], v[196:197], v[192:193] op_sel_hi:[1,0,1]
	v_pk_fma_f32 v[78:79], v[78:79], v[196:197], v[190:191] op_sel_hi:[1,0,1]
	v_pk_fma_f32 v[72:73], v[72:73], v[196:197], v[188:189] op_sel_hi:[1,0,1]
	v_pk_fma_f32 v[70:71], v[70:71], v[196:197], v[186:187] op_sel_hi:[1,0,1]
	v_cndmask_b32_e64 v73, v73, v245, s[16:17]
	v_cndmask_b32_e64 v71, v71, v245, s[16:17]
	v_cndmask_b32_e64 v70, v70, v245, s[16:17]
	v_cndmask_b32_e64 v72, v72, v245, s[16:17]
	v_cndmask_b32_e64 v79, v79, v245, s[16:17]
	v_cndmask_b32_e64 v78, v78, v245, s[16:17]
	v_cndmask_b32_e64 v81, v81, v245, s[16:17]
	v_cndmask_b32_e64 v80, v80, v245, s[16:17]
	s_and_b64 vcc, exec, s[20:21]
	v_lshl_add_u64 v[192:193], v[194:195], 2, s[60:61]
	s_cbranch_vccnz .LBB0_588
	global_store_dwordx4 v[192:193], v[78:81], off
	global_store_dwordx4 v[192:193], v[70:73], off offset:16
	v_lshl_add_u64 v[190:191], v[194:195], 1, s[78:79]
	s_cbranch_execnz .LBB0_487

.LBB0_489:
	v_lshlrev_b32_e32 v186, 16, v178
	v_and_b32_e32 v187, 0xffff0000, v178
	v_lshlrev_b32_e32 v188, 16, v179
	v_and_b32_e32 v189, 0xffff0000, v179
	v_lshlrev_b32_e32 v182, 16, v180
	v_and_b32_e32 v183, 0xffff0000, v180
	v_lshlrev_b32_e32 v184, 16, v181
	v_and_b32_e32 v185, 0xffff0000, v181
.LBB0_490:
	v_mov_b32_e32 v197, v196
	v_pk_mul_f32 v[104:105], v[104:105], v[140:141]
	v_pk_mul_f32 v[102:103], v[102:103], v[138:139]
	v_mov_b32_e32 v178, v196
	v_mov_b32_e32 v179, v196
	v_pk_mul_f32 v[100:101], v[100:101], v[136:137]
	v_pk_mul_f32 v[98:99], v[98:99], v[134:135]
	v_pk_fma_f32 v[104:105], v[104:105], v[178:179], v[188:189]
	v_pk_fma_f32 v[102:103], v[102:103], v[196:197], v[186:187]
	v_pk_fma_f32 v[100:101], v[100:101], v[178:179], v[184:185]
	v_pk_fma_f32 v[98:99], v[98:99], v[196:197], v[182:183]
	v_cndmask_b32_e64 v101, v101, v245, s[16:17]
	v_cndmask_b32_e64 v100, v100, v245, s[16:17]
	v_cndmask_b32_e64 v99, v99, v245, s[16:17]
	v_cndmask_b32_e64 v98, v98, v245, s[16:17]
	v_cndmask_b32_e64 v105, v105, v245, s[16:17]
	v_cndmask_b32_e64 v104, v104, v245, s[16:17]
	v_cndmask_b32_e64 v103, v103, v245, s[16:17]
	s_and_b64 vcc, exec, s[20:21]
	v_cndmask_b32_e64 v102, v102, v245, s[16:17]
	s_cbranch_vccnz .LBB0_589
	global_store_dwordx4 v[192:193], v[102:105], off offset:512
	global_store_dwordx4 v[192:193], v[98:101], off offset:528
	s_cbranch_execnz .LBB0_493

.LBB0_493:
	ds_read_b32 v188, v234 offset:9216
	s_nop 0
	v_add_u32_e32 v178, 0x80, v228
	v_ashrrev_i32_e32 v179, 31, v178
	v_lshlrev_b64 v[186:187], 11, v[178:179]
	v_or_b32_e32 v186, v186, v239
	s_mov_b64 s[66:67], -1
	s_and_b64 vcc, exec, s[18:19]
	v_lshl_add_u64 v[190:191], v[186:187], 2, s[22:23]
	s_cbranch_vccnz .LBB0_495
	global_load_dwordx4 v[178:181], v[190:191], off offset:16
	global_load_dwordx4 v[182:185], v[190:191], off
	s_waitcnt vmcnt(0)
	s_mov_b64 s[66:67], 0
.LBB0_495:
	s_andn2_b64 vcc, exec, s[66:67]
	s_cbranch_vccnz .LBB0_497
	v_lshlrev_b32_e32 v182, 16, v174
	v_and_b32_e32 v183, 0xffff0000, v174
	v_lshlrev_b32_e32 v184, 16, v175
	v_and_b32_e32 v185, 0xffff0000, v175
	v_lshlrev_b32_e32 v178, 16, v176
	v_and_b32_e32 v179, 0xffff0000, v176
	v_lshlrev_b32_e32 v180, 16, v177
	v_and_b32_e32 v181, 0xffff0000, v177
.LBB0_497:
	v_pk_mul_f32 v[96:97], v[96:97], v[152:153]
	v_pk_mul_f32 v[94:95], v[94:95], v[150:151]
	v_pk_mul_f32 v[92:93], v[92:93], v[148:149]
	v_pk_mul_f32 v[90:91], v[90:91], v[146:147]
	s_waitcnt lgkmcnt(0)
	v_pk_fma_f32 v[96:97], v[96:97], v[188:189], v[184:185] op_sel_hi:[1,0,1]
	v_pk_fma_f32 v[94:95], v[94:95], v[188:189], v[182:183] op_sel_hi:[1,0,1]
	v_pk_fma_f32 v[92:93], v[92:93], v[188:189], v[180:181] op_sel_hi:[1,0,1]
	v_pk_fma_f32 v[90:91], v[90:91], v[188:189], v[178:179] op_sel_hi:[1,0,1]
	v_cndmask_b32_e64 v93, v93, v245, s[16:17]
	v_cndmask_b32_e64 v91, v91, v245, s[16:17]
	v_cndmask_b32_e64 v90, v90, v245, s[16:17]
	v_cndmask_b32_e64 v92, v92, v245, s[16:17]
	v_cndmask_b32_e64 v95, v95, v245, s[16:17]
	v_cndmask_b32_e64 v94, v94, v245, s[16:17]
	v_cndmask_b32_e64 v97, v97, v245, s[16:17]
	v_cndmask_b32_e64 v96, v96, v245, s[16:17]
	s_and_b64 vcc, exec, s[20:21]
	v_lshl_add_u64 v[184:185], v[186:187], 2, s[60:61]
	s_cbranch_vccnz .LBB0_590
	global_store_dwordx4 v[184:185], v[94:97], off
	global_store_dwordx4 v[184:185], v[90:93], off offset:16
	v_lshl_add_u64 v[182:183], v[186:187], 1, s[78:79]
	s_cbranch_execnz .LBB0_500

.LBB0_502:
	v_lshlrev_b32_e32 v178, 16, v170
	v_and_b32_e32 v179, 0xffff0000, v170
	v_lshlrev_b32_e32 v180, 16, v171
	v_and_b32_e32 v181, 0xffff0000, v171
	v_lshlrev_b32_e32 v174, 16, v172
	v_and_b32_e32 v175, 0xffff0000, v172
	v_lshlrev_b32_e32 v176, 16, v173
	v_and_b32_e32 v177, 0xffff0000, v173
.LBB0_503:
	v_mov_b32_e32 v189, v188
	v_pk_mul_f32 v[128:129], v[128:129], v[140:141]
	v_pk_mul_f32 v[126:127], v[126:127], v[138:139]
	v_mov_b32_e32 v170, v188
	v_mov_b32_e32 v171, v188
	v_pk_mul_f32 v[120:121], v[120:121], v[136:137]
	v_pk_mul_f32 v[118:119], v[118:119], v[134:135]
	v_pk_fma_f32 v[128:129], v[128:129], v[170:171], v[180:181]
	v_pk_fma_f32 v[126:127], v[126:127], v[188:189], v[178:179]
	v_pk_fma_f32 v[120:121], v[120:121], v[170:171], v[176:177]
	v_pk_fma_f32 v[118:119], v[118:119], v[188:189], v[174:175]
	v_cndmask_b32_e64 v121, v121, v245, s[16:17]
	v_cndmask_b32_e64 v120, v120, v245, s[16:17]
	v_cndmask_b32_e64 v119, v119, v245, s[16:17]
	v_cndmask_b32_e64 v118, v118, v245, s[16:17]
	v_cndmask_b32_e64 v129, v129, v245, s[16:17]
	v_cndmask_b32_e64 v128, v128, v245, s[16:17]
	v_cndmask_b32_e64 v127, v127, v245, s[16:17]
	s_and_b64 vcc, exec, s[20:21]
	v_cndmask_b32_e64 v126, v126, v245, s[16:17]
	s_cbranch_vccnz .LBB0_591
	global_store_dwordx4 v[184:185], v[126:129], off offset:512
	global_store_dwordx4 v[184:185], v[118:121], off offset:528
	s_cbranch_execnz .LBB0_506

.LBB0_506:
	ds_read_b32 v180, v234 offset:9344
	s_nop 0
	v_add_u32_e32 v170, 0x90, v228
	v_ashrrev_i32_e32 v171, 31, v170
	v_lshlrev_b64 v[178:179], 11, v[170:171]
	v_or_b32_e32 v178, v178, v239
	s_mov_b64 s[66:67], -1
	s_and_b64 vcc, exec, s[18:19]
	v_lshl_add_u64 v[182:183], v[178:179], 2, s[22:23]
	s_cbranch_vccnz .LBB0_508
	global_load_dwordx4 v[170:173], v[182:183], off offset:16
	global_load_dwordx4 v[174:177], v[182:183], off
	s_waitcnt vmcnt(0)
	s_mov_b64 s[66:67], 0
.LBB0_508:
	s_andn2_b64 vcc, exec, s[66:67]
	s_cbranch_vccnz .LBB0_510
	v_lshlrev_b32_e32 v174, 16, v166
	v_and_b32_e32 v175, 0xffff0000, v166
	v_lshlrev_b32_e32 v176, 16, v167
	v_and_b32_e32 v177, 0xffff0000, v167
	v_lshlrev_b32_e32 v170, 16, v168
	v_and_b32_e32 v171, 0xffff0000, v168
	v_lshlrev_b32_e32 v172, 16, v169
	v_and_b32_e32 v173, 0xffff0000, v169
.LBB0_510:
	v_pk_mul_f32 v[116:117], v[116:117], v[152:153]
	v_pk_mul_f32 v[114:115], v[114:115], v[150:151]
	v_pk_mul_f32 v[108:109], v[108:109], v[148:149]
	v_pk_mul_f32 v[106:107], v[106:107], v[146:147]
	s_waitcnt lgkmcnt(0)
	v_pk_fma_f32 v[116:117], v[116:117], v[180:181], v[176:177] op_sel_hi:[1,0,1]
	v_pk_fma_f32 v[114:115], v[114:115], v[180:181], v[174:175] op_sel_hi:[1,0,1]
	v_pk_fma_f32 v[108:109], v[108:109], v[180:181], v[172:173] op_sel_hi:[1,0,1]
	v_pk_fma_f32 v[106:107], v[106:107], v[180:181], v[170:171] op_sel_hi:[1,0,1]
	v_cndmask_b32_e64 v109, v109, v245, s[16:17]
	v_cndmask_b32_e64 v107, v107, v245, s[16:17]
	v_cndmask_b32_e64 v106, v106, v245, s[16:17]
	v_cndmask_b32_e64 v108, v108, v245, s[16:17]
	v_cndmask_b32_e64 v115, v115, v245, s[16:17]
	v_cndmask_b32_e64 v114, v114, v245, s[16:17]
	v_cndmask_b32_e64 v117, v117, v245, s[16:17]
	v_cndmask_b32_e64 v116, v116, v245, s[16:17]
	s_and_b64 vcc, exec, s[20:21]
	v_lshl_add_u64 v[176:177], v[178:179], 2, s[60:61]
	s_cbranch_vccnz .LBB0_592
	global_store_dwordx4 v[176:177], v[114:117], off
	global_store_dwordx4 v[176:177], v[106:109], off offset:16
	v_lshl_add_u64 v[174:175], v[178:179], 1, s[78:79]
	s_cbranch_execnz .LBB0_513

.LBB0_515:
	v_lshlrev_b32_e32 v170, 16, v162
	v_and_b32_e32 v171, 0xffff0000, v162
	v_lshlrev_b32_e32 v172, 16, v163
	v_and_b32_e32 v173, 0xffff0000, v163
	v_lshlrev_b32_e32 v166, 16, v164
	v_and_b32_e32 v167, 0xffff0000, v164
	v_lshlrev_b32_e32 v168, 16, v165
	v_and_b32_e32 v169, 0xffff0000, v165
.LBB0_516:
	v_mov_b32_e32 v181, v180
	v_pk_mul_f32 v[124:125], v[124:125], v[140:141]
	v_pk_mul_f32 v[122:123], v[122:123], v[138:139]
	v_mov_b32_e32 v162, v180
	v_mov_b32_e32 v163, v180
	v_pk_mul_f32 v[112:113], v[112:113], v[136:137]
	v_pk_mul_f32 v[110:111], v[110:111], v[134:135]
	v_pk_fma_f32 v[124:125], v[124:125], v[162:163], v[172:173]
	v_pk_fma_f32 v[122:123], v[122:123], v[180:181], v[170:171]
	v_pk_fma_f32 v[112:113], v[112:113], v[162:163], v[168:169]
	v_pk_fma_f32 v[110:111], v[110:111], v[180:181], v[166:167]
	v_cndmask_b32_e64 v113, v113, v245, s[16:17]
	v_cndmask_b32_e64 v112, v112, v245, s[16:17]
	v_cndmask_b32_e64 v111, v111, v245, s[16:17]
	v_cndmask_b32_e64 v110, v110, v245, s[16:17]
	v_cndmask_b32_e64 v125, v125, v245, s[16:17]
	v_cndmask_b32_e64 v124, v124, v245, s[16:17]
	v_cndmask_b32_e64 v123, v123, v245, s[16:17]
	s_and_b64 vcc, exec, s[20:21]
	v_cndmask_b32_e64 v122, v122, v245, s[16:17]
	s_cbranch_vccnz .LBB0_593
	global_store_dwordx4 v[176:177], v[122:125], off offset:512
	global_store_dwordx4 v[176:177], v[110:113], off offset:528
	s_cbranch_execnz .LBB0_519

.LBB0_519:
	ds_read_b32 v172, v234 offset:9472
	s_nop 0
	v_add_u32_e32 v162, 0xa0, v228
	v_ashrrev_i32_e32 v163, 31, v162
	v_lshlrev_b64 v[170:171], 11, v[162:163]
	v_or_b32_e32 v170, v170, v239
	s_mov_b64 s[66:67], -1
	s_and_b64 vcc, exec, s[18:19]
	v_lshl_add_u64 v[174:175], v[170:171], 2, s[22:23]
	s_cbranch_vccnz .LBB0_521
	global_load_dwordx4 v[162:165], v[174:175], off offset:16
	global_load_dwordx4 v[166:169], v[174:175], off
	s_waitcnt vmcnt(0)
	s_mov_b64 s[66:67], 0
.LBB0_521:
	s_andn2_b64 vcc, exec, s[66:67]
	s_cbranch_vccnz .LBB0_523
	v_lshlrev_b32_e32 v166, 16, v158
	v_and_b32_e32 v167, 0xffff0000, v158
	v_lshlrev_b32_e32 v168, 16, v159
	v_and_b32_e32 v169, 0xffff0000, v159
	v_lshlrev_b32_e32 v162, 16, v160
	v_and_b32_e32 v163, 0xffff0000, v160
	v_lshlrev_b32_e32 v164, 16, v161
	v_and_b32_e32 v165, 0xffff0000, v161
.LBB0_523:
	v_pk_mul_f32 v[76:77], v[76:77], v[152:153]
	v_pk_mul_f32 v[74:75], v[74:75], v[150:151]
	v_pk_mul_f32 v[68:69], v[68:69], v[148:149]
	v_pk_mul_f32 v[66:67], v[66:67], v[146:147]
	s_waitcnt lgkmcnt(0)
	v_pk_fma_f32 v[76:77], v[76:77], v[172:173], v[168:169] op_sel_hi:[1,0,1]
	v_pk_fma_f32 v[74:75], v[74:75], v[172:173], v[166:167] op_sel_hi:[1,0,1]
	v_pk_fma_f32 v[68:69], v[68:69], v[172:173], v[164:165] op_sel_hi:[1,0,1]
	v_pk_fma_f32 v[66:67], v[66:67], v[172:173], v[162:163] op_sel_hi:[1,0,1]
	v_cndmask_b32_e64 v69, v69, v245, s[16:17]
	v_cndmask_b32_e64 v67, v67, v245, s[16:17]
	v_cndmask_b32_e64 v66, v66, v245, s[16:17]
	v_cndmask_b32_e64 v68, v68, v245, s[16:17]
	v_cndmask_b32_e64 v75, v75, v245, s[16:17]
	v_cndmask_b32_e64 v74, v74, v245, s[16:17]
	v_cndmask_b32_e64 v77, v77, v245, s[16:17]
	v_cndmask_b32_e64 v76, v76, v245, s[16:17]
	s_and_b64 vcc, exec, s[20:21]
	v_lshl_add_u64 v[168:169], v[170:171], 2, s[60:61]
	s_cbranch_vccnz .LBB0_594
	global_store_dwordx4 v[168:169], v[74:77], off
	global_store_dwordx4 v[168:169], v[66:69], off offset:16
	v_lshl_add_u64 v[166:167], v[170:171], 1, s[78:79]
	s_cbranch_execnz .LBB0_526

.LBB0_528:
	v_lshlrev_b32_e32 v162, 16, v154
	v_and_b32_e32 v163, 0xffff0000, v154
	v_lshlrev_b32_e32 v164, 16, v155
	v_and_b32_e32 v165, 0xffff0000, v155
	v_lshlrev_b32_e32 v158, 16, v156
	v_and_b32_e32 v159, 0xffff0000, v156
	v_lshlrev_b32_e32 v160, 16, v157
	v_and_b32_e32 v161, 0xffff0000, v157
.LBB0_529:
	v_mov_b32_e32 v173, v172
	v_pk_mul_f32 v[32:33], v[32:33], v[140:141]
	v_pk_mul_f32 v[30:31], v[30:31], v[138:139]
	v_mov_b32_e32 v154, v172
	v_mov_b32_e32 v155, v172
	v_pk_mul_f32 v[24:25], v[24:25], v[136:137]
	v_pk_mul_f32 v[22:23], v[22:23], v[134:135]
	v_pk_fma_f32 v[32:33], v[32:33], v[154:155], v[164:165]
	v_pk_fma_f32 v[30:31], v[30:31], v[172:173], v[162:163]
	v_pk_fma_f32 v[24:25], v[24:25], v[154:155], v[160:161]
	v_pk_fma_f32 v[22:23], v[22:23], v[172:173], v[158:159]
	v_cndmask_b32_e64 v25, v25, v245, s[16:17]
	v_cndmask_b32_e64 v24, v24, v245, s[16:17]
	v_cndmask_b32_e64 v23, v23, v245, s[16:17]
	v_cndmask_b32_e64 v22, v22, v245, s[16:17]
	v_cndmask_b32_e64 v33, v33, v245, s[16:17]
	v_cndmask_b32_e64 v32, v32, v245, s[16:17]
	v_cndmask_b32_e64 v31, v31, v245, s[16:17]
	s_and_b64 vcc, exec, s[20:21]
	v_cndmask_b32_e64 v30, v30, v245, s[16:17]
	s_cbranch_vccnz .LBB0_595
	global_store_dwordx4 v[168:169], v[30:33], off offset:512
	global_store_dwordx4 v[168:169], v[22:25], off offset:528
	s_cbranch_execnz .LBB0_532

.LBB0_532:
	ds_read_b32 v164, v234 offset:9600
	s_nop 0
	v_add_u32_e32 v154, 0xb0, v228
	v_ashrrev_i32_e32 v155, 31, v154
	v_lshlrev_b64 v[162:163], 11, v[154:155]
	v_or_b32_e32 v162, v162, v239
	s_mov_b64 s[66:67], -1
	s_and_b64 vcc, exec, s[18:19]
	v_lshl_add_u64 v[166:167], v[162:163], 2, s[22:23]
	s_cbranch_vccnz .LBB0_534
	global_load_dwordx4 v[154:157], v[166:167], off offset:16
	global_load_dwordx4 v[158:161], v[166:167], off
	s_waitcnt vmcnt(0)
	s_mov_b64 s[66:67], 0
.LBB0_534:
	s_andn2_b64 vcc, exec, s[66:67]
	s_cbranch_vccnz .LBB0_536
	v_lshlrev_b32_e32 v158, 16, v142
	v_and_b32_e32 v159, 0xffff0000, v142
	v_lshlrev_b32_e32 v160, 16, v143
	v_and_b32_e32 v161, 0xffff0000, v143
	v_lshlrev_b32_e32 v154, 16, v144
	v_and_b32_e32 v155, 0xffff0000, v144
	v_lshlrev_b32_e32 v156, 16, v145
	v_and_b32_e32 v157, 0xffff0000, v145
.LBB0_536:
	v_pk_mul_f32 v[16:17], v[16:17], v[152:153]
	v_pk_mul_f32 v[14:15], v[14:15], v[150:151]
	v_pk_mul_f32 v[12:13], v[12:13], v[148:149]
	v_pk_mul_f32 v[10:11], v[10:11], v[146:147]
	s_waitcnt lgkmcnt(0)
	v_pk_fma_f32 v[16:17], v[16:17], v[164:165], v[160:161] op_sel_hi:[1,0,1]
	v_pk_fma_f32 v[14:15], v[14:15], v[164:165], v[158:159] op_sel_hi:[1,0,1]
	v_pk_fma_f32 v[12:13], v[12:13], v[164:165], v[156:157] op_sel_hi:[1,0,1]
	v_pk_fma_f32 v[10:11], v[10:11], v[164:165], v[154:155] op_sel_hi:[1,0,1]
	v_cndmask_b32_e64 v13, v13, v245, s[16:17]
	v_cndmask_b32_e64 v11, v11, v245, s[16:17]
	v_cndmask_b32_e64 v10, v10, v245, s[16:17]
	v_cndmask_b32_e64 v12, v12, v245, s[16:17]
	v_cndmask_b32_e64 v15, v15, v245, s[16:17]
	v_cndmask_b32_e64 v14, v14, v245, s[16:17]
	v_cndmask_b32_e64 v17, v17, v245, s[16:17]
	v_cndmask_b32_e64 v16, v16, v245, s[16:17]
	s_and_b64 vcc, exec, s[20:21]
	v_lshl_add_u64 v[152:153], v[162:163], 2, s[60:61]
	s_cbranch_vccnz .LBB0_596
	global_store_dwordx4 v[152:153], v[14:17], off
	global_store_dwordx4 v[152:153], v[10:13], off offset:16
	v_lshl_add_u64 v[150:151], v[162:163], 1, s[78:79]
	s_cbranch_execnz .LBB0_539

.LBB0_541:
	v_lshlrev_b32_e32 v146, 16, v130
	v_and_b32_e32 v147, 0xffff0000, v130
	v_lshlrev_b32_e32 v148, 16, v131
	v_and_b32_e32 v149, 0xffff0000, v131
	v_lshlrev_b32_e32 v142, 16, v132
	v_and_b32_e32 v143, 0xffff0000, v132
	v_lshlrev_b32_e32 v144, 16, v133
	v_and_b32_e32 v145, 0xffff0000, v133
.LBB0_542:
	v_mov_b32_e32 v165, v164
	v_pk_mul_f32 v[8:9], v[8:9], v[140:141]
	v_pk_mul_f32 v[6:7], v[6:7], v[138:139]
	v_mov_b32_e32 v130, v164
	v_mov_b32_e32 v131, v164
	v_pk_mul_f32 v[4:5], v[4:5], v[136:137]
	v_pk_mul_f32 v[2:3], v[2:3], v[134:135]
	v_pk_fma_f32 v[8:9], v[8:9], v[130:131], v[148:149]
	v_pk_fma_f32 v[6:7], v[6:7], v[164:165], v[146:147]
	v_pk_fma_f32 v[4:5], v[4:5], v[130:131], v[144:145]
	v_pk_fma_f32 v[2:3], v[2:3], v[164:165], v[142:143]
	v_cndmask_b32_e64 v5, v5, v245, s[16:17]
	v_cndmask_b32_e64 v4, v4, v245, s[16:17]
	v_cndmask_b32_e64 v3, v3, v245, s[16:17]
	v_cndmask_b32_e64 v2, v2, v245, s[16:17]
	v_cndmask_b32_e64 v9, v9, v245, s[16:17]
	v_cndmask_b32_e64 v8, v8, v245, s[16:17]
	v_cndmask_b32_e64 v7, v7, v245, s[16:17]
	s_and_b64 vcc, exec, s[20:21]
	v_cndmask_b32_e64 v6, v6, v245, s[16:17]
	s_cbranch_vccnz .LBB0_597
	global_store_dwordx4 v[152:153], v[6:9], off offset:512
	global_store_dwordx4 v[152:153], v[2:5], off offset:528
	s_cbranch_execnz .LBB0_545

.LBB0_574:
	global_load_dwordx4 v[206:209], v[232:233], off offset:528
	global_load_dwordx4 v[210:213], v[232:233], off offset:512
	s_waitcnt vmcnt(0)
	s_cbranch_execz .LBB0_450
	s_branch .LBB0_451
.LBB0_575:
	global_load_dwordx4 v[198:201], v[214:215], off offset:528
	global_load_dwordx4 v[202:205], v[214:215], off offset:512
	s_waitcnt vmcnt(0)
	s_cbranch_execz .LBB0_463
	s_branch .LBB0_464
.LBB0_576:
	global_load_dwordx4 v[190:193], v[206:207], off offset:528
	global_load_dwordx4 v[194:197], v[206:207], off offset:512
	s_waitcnt vmcnt(0)
	s_cbranch_execz .LBB0_476
	s_branch .LBB0_477
.LBB0_577:
	global_load_dwordx4 v[182:185], v[198:199], off offset:528
	global_load_dwordx4 v[186:189], v[198:199], off offset:512
	s_waitcnt vmcnt(0)
	s_cbranch_execz .LBB0_489
	s_branch .LBB0_490
.LBB0_578:
	global_load_dwordx4 v[174:177], v[190:191], off offset:528
	global_load_dwordx4 v[178:181], v[190:191], off offset:512
	s_waitcnt vmcnt(0)
	s_cbranch_execz .LBB0_502
	s_branch .LBB0_503
.LBB0_579:
	global_load_dwordx4 v[166:169], v[182:183], off offset:528
	global_load_dwordx4 v[170:173], v[182:183], off offset:512
	s_waitcnt vmcnt(0)
	s_cbranch_execz .LBB0_515
	s_branch .LBB0_516
.LBB0_580:
	global_load_dwordx4 v[158:161], v[174:175], off offset:528
	global_load_dwordx4 v[162:165], v[174:175], off offset:512
	s_waitcnt vmcnt(0)
	s_cbranch_execz .LBB0_528
	s_branch .LBB0_529
.LBB0_581:
	global_load_dwordx4 v[142:145], v[166:167], off offset:528
	global_load_dwordx4 v[146:149], v[166:167], off offset:512
	s_waitcnt vmcnt(0)
	s_cbranch_execz .LBB0_541
	s_branch .LBB0_542

.LBB0_1246:
	v_mov_b32_e32 v231, v230
	v_pk_mul_f32 v[44:45], v[44:45], v[140:141]
	v_pk_mul_f32 v[42:43], v[42:43], v[138:139]
	v_mov_b32_e32 v202, v230
	v_mov_b32_e32 v203, v230
	v_pk_mul_f32 v[36:37], v[36:37], v[136:137]
	v_pk_mul_f32 v[34:35], v[34:35], v[134:135]
	v_pk_fma_f32 v[44:45], v[44:45], v[202:203], v[212:213]
	v_pk_fma_f32 v[42:43], v[42:43], v[230:231], v[210:211]
	v_pk_fma_f32 v[36:37], v[36:37], v[202:203], v[208:209]
	v_pk_fma_f32 v[34:35], v[34:35], v[230:231], v[206:207]
	v_cndmask_b32_e64 v202, 0, 1, s[76:77]
	v_cndmask_b32_e64 v37, v37, v245, s[14:15]
	v_cndmask_b32_e64 v36, v36, v245, s[14:15]
	v_cndmask_b32_e64 v35, v35, v245, s[14:15]
	v_cndmask_b32_e64 v34, v34, v245, s[14:15]
	v_cndmask_b32_e64 v45, v45, v245, s[14:15]
	v_cndmask_b32_e64 v44, v44, v245, s[14:15]
	v_cndmask_b32_e64 v43, v43, v245, s[14:15]
	v_cmp_ne_u32_e64 s[18:19], 1, v202
	s_andn2_b64 vcc, exec, s[76:77]
	v_cndmask_b32_e64 v42, v42, v245, s[14:15]
	s_cbranch_vccnz .LBB0_1378
	global_store_dwordx4 v[216:217], v[42:45], off offset:512
	global_store_dwordx4 v[216:217], v[34:37], off offset:528
	s_cbranch_execnz .LBB0_1249

.LBB0_1249:
	ds_read_b32 v212, v235 offset:8320
	s_nop 0
	v_add3_u32 v202, s44, v218, 16
	v_ashrrev_i32_e32 v203, 31, v202
	v_lshlrev_b64 v[210:211], 11, v[202:203]
	v_or_b32_e32 v210, v210, v239
	s_mov_b64 s[66:67], -1
	s_and_b64 vcc, exec, s[16:17]
	v_lshl_add_u64 v[214:215], v[210:211], 2, s[22:23]
	s_cbranch_vccnz .LBB0_1251
	global_load_dwordx4 v[202:205], v[214:215], off offset:16
	global_load_dwordx4 v[206:209], v[214:215], off
	s_waitcnt vmcnt(0)
	s_mov_b64 s[66:67], 0

.LBB0_1253:
	v_pk_mul_f32 v[56:57], v[56:57], v[152:153]
	v_pk_mul_f32 v[54:55], v[54:55], v[150:151]
	v_pk_mul_f32 v[52:53], v[52:53], v[148:149]
	v_pk_mul_f32 v[50:51], v[50:51], v[146:147]
	s_waitcnt lgkmcnt(0)
	v_pk_fma_f32 v[56:57], v[56:57], v[212:213], v[208:209] op_sel_hi:[1,0,1]
	v_pk_fma_f32 v[54:55], v[54:55], v[212:213], v[206:207] op_sel_hi:[1,0,1]
	v_pk_fma_f32 v[52:53], v[52:53], v[212:213], v[204:205] op_sel_hi:[1,0,1]
	v_pk_fma_f32 v[50:51], v[50:51], v[212:213], v[202:203] op_sel_hi:[1,0,1]
	v_cndmask_b32_e64 v53, v53, v245, s[14:15]
	v_cndmask_b32_e64 v51, v51, v245, s[14:15]
	v_cndmask_b32_e64 v50, v50, v245, s[14:15]
	v_cndmask_b32_e64 v52, v52, v245, s[14:15]
	v_cndmask_b32_e64 v55, v55, v245, s[14:15]
	v_cndmask_b32_e64 v54, v54, v245, s[14:15]
	v_cndmask_b32_e64 v57, v57, v245, s[14:15]
	v_cndmask_b32_e64 v56, v56, v245, s[14:15]
	s_and_b64 vcc, exec, s[18:19]
	v_lshl_add_u64 v[208:209], v[210:211], 2, s[60:61]
	s_cbranch_vccnz .LBB0_1379
	global_store_dwordx4 v[208:209], v[54:57], off
	global_store_dwordx4 v[208:209], v[50:53], off offset:16
	v_lshl_add_u64 v[206:207], v[210:211], 1, s[56:57]
	s_cbranch_execnz .LBB0_1256

.LBB0_1259:
	v_mov_b32_e32 v213, v212
	v_pk_mul_f32 v[68:69], v[68:69], v[140:141]
	v_pk_mul_f32 v[66:67], v[66:67], v[138:139]
	v_mov_b32_e32 v194, v212
	v_mov_b32_e32 v195, v212
	v_pk_mul_f32 v[60:61], v[60:61], v[136:137]
	v_pk_mul_f32 v[58:59], v[58:59], v[134:135]
	v_pk_fma_f32 v[68:69], v[68:69], v[194:195], v[204:205]
	v_pk_fma_f32 v[66:67], v[66:67], v[212:213], v[202:203]
	v_pk_fma_f32 v[60:61], v[60:61], v[194:195], v[200:201]
	v_pk_fma_f32 v[58:59], v[58:59], v[212:213], v[198:199]
	v_cndmask_b32_e64 v61, v61, v245, s[14:15]
	v_cndmask_b32_e64 v60, v60, v245, s[14:15]
	v_cndmask_b32_e64 v59, v59, v245, s[14:15]
	v_cndmask_b32_e64 v58, v58, v245, s[14:15]
	v_cndmask_b32_e64 v69, v69, v245, s[14:15]
	v_cndmask_b32_e64 v68, v68, v245, s[14:15]
	v_cndmask_b32_e64 v67, v67, v245, s[14:15]
	s_and_b64 vcc, exec, s[18:19]
	v_cndmask_b32_e64 v66, v66, v245, s[14:15]
	s_cbranch_vccnz .LBB0_1380
	global_store_dwordx4 v[208:209], v[66:69], off offset:512
	global_store_dwordx4 v[208:209], v[58:61], off offset:528
	s_cbranch_execnz .LBB0_1262

.LBB0_1262:
	ds_read_b32 v204, v235 offset:8448
	s_nop 0
	v_add3_u32 v194, s44, v218, 32
	v_ashrrev_i32_e32 v195, 31, v194
	v_lshlrev_b64 v[202:203], 11, v[194:195]
	v_or_b32_e32 v202, v202, v239
	s_mov_b64 s[66:67], -1
	s_and_b64 vcc, exec, s[16:17]
	v_lshl_add_u64 v[206:207], v[202:203], 2, s[22:23]
	s_cbranch_vccnz .LBB0_1264
	global_load_dwordx4 v[194:197], v[206:207], off offset:16
	global_load_dwordx4 v[198:201], v[206:207], off
	s_waitcnt vmcnt(0)
	s_mov_b64 s[66:67], 0

.LBB0_1266:
	v_pk_mul_f32 v[80:81], v[80:81], v[152:153]
	v_pk_mul_f32 v[78:79], v[78:79], v[150:151]
	v_pk_mul_f32 v[76:77], v[76:77], v[148:149]
	v_pk_mul_f32 v[74:75], v[74:75], v[146:147]
	s_waitcnt lgkmcnt(0)
	v_pk_fma_f32 v[80:81], v[80:81], v[204:205], v[200:201] op_sel_hi:[1,0,1]
	v_pk_fma_f32 v[78:79], v[78:79], v[204:205], v[198:199] op_sel_hi:[1,0,1]
	v_pk_fma_f32 v[76:77], v[76:77], v[204:205], v[196:197] op_sel_hi:[1,0,1]
	v_pk_fma_f32 v[74:75], v[74:75], v[204:205], v[194:195] op_sel_hi:[1,0,1]
	v_cndmask_b32_e64 v77, v77, v245, s[14:15]
	v_cndmask_b32_e64 v75, v75, v245, s[14:15]
	v_cndmask_b32_e64 v74, v74, v245, s[14:15]
	v_cndmask_b32_e64 v76, v76, v245, s[14:15]
	v_cndmask_b32_e64 v79, v79, v245, s[14:15]
	v_cndmask_b32_e64 v78, v78, v245, s[14:15]
	v_cndmask_b32_e64 v81, v81, v245, s[14:15]
	v_cndmask_b32_e64 v80, v80, v245, s[14:15]
	s_and_b64 vcc, exec, s[18:19]
	v_lshl_add_u64 v[200:201], v[202:203], 2, s[60:61]
	s_cbranch_vccnz .LBB0_1381
	global_store_dwordx4 v[200:201], v[78:81], off
	global_store_dwordx4 v[200:201], v[74:77], off offset:16
	v_lshl_add_u64 v[198:199], v[202:203], 1, s[56:57]
	s_cbranch_execnz .LBB0_1269

.LBB0_1272:
	v_mov_b32_e32 v205, v204
	v_pk_mul_f32 v[88:89], v[88:89], v[140:141]
	v_pk_mul_f32 v[86:87], v[86:87], v[138:139]
	v_mov_b32_e32 v186, v204
	v_mov_b32_e32 v187, v204
	v_pk_mul_f32 v[84:85], v[84:85], v[136:137]
	v_pk_mul_f32 v[82:83], v[82:83], v[134:135]
	v_pk_fma_f32 v[88:89], v[88:89], v[186:187], v[196:197]
	v_pk_fma_f32 v[86:87], v[86:87], v[204:205], v[194:195]
	v_pk_fma_f32 v[84:85], v[84:85], v[186:187], v[192:193]
	v_pk_fma_f32 v[82:83], v[82:83], v[204:205], v[190:191]
	v_cndmask_b32_e64 v85, v85, v245, s[14:15]
	v_cndmask_b32_e64 v84, v84, v245, s[14:15]
	v_cndmask_b32_e64 v83, v83, v245, s[14:15]
	v_cndmask_b32_e64 v82, v82, v245, s[14:15]
	v_cndmask_b32_e64 v89, v89, v245, s[14:15]
	v_cndmask_b32_e64 v88, v88, v245, s[14:15]
	v_cndmask_b32_e64 v87, v87, v245, s[14:15]
	s_and_b64 vcc, exec, s[18:19]
	v_cndmask_b32_e64 v86, v86, v245, s[14:15]
	s_cbranch_vccnz .LBB0_1382
	global_store_dwordx4 v[200:201], v[86:89], off offset:512
	global_store_dwordx4 v[200:201], v[82:85], off offset:528
	s_cbranch_execnz .LBB0_1275

.LBB0_1275:
	ds_read_b32 v196, v235 offset:8576
	s_nop 0
	v_add3_u32 v186, s44, v218, 48
	v_ashrrev_i32_e32 v187, 31, v186
	v_lshlrev_b64 v[194:195], 11, v[186:187]
	v_or_b32_e32 v194, v194, v239
	s_mov_b64 s[66:67], -1
	s_and_b64 vcc, exec, s[16:17]
	v_lshl_add_u64 v[198:199], v[194:195], 2, s[22:23]
	s_cbranch_vccnz .LBB0_1277
	global_load_dwordx4 v[186:189], v[198:199], off offset:16
	global_load_dwordx4 v[190:193], v[198:199], off
	s_waitcnt vmcnt(0)
	s_mov_b64 s[66:67], 0

.LBB0_1279:
	v_pk_mul_f32 v[104:105], v[104:105], v[152:153]
	v_pk_mul_f32 v[102:103], v[102:103], v[150:151]
	v_pk_mul_f32 v[96:97], v[96:97], v[148:149]
	v_pk_mul_f32 v[94:95], v[94:95], v[146:147]
	s_waitcnt lgkmcnt(0)
	v_pk_fma_f32 v[104:105], v[104:105], v[196:197], v[192:193] op_sel_hi:[1,0,1]
	v_pk_fma_f32 v[102:103], v[102:103], v[196:197], v[190:191] op_sel_hi:[1,0,1]
	v_pk_fma_f32 v[96:97], v[96:97], v[196:197], v[188:189] op_sel_hi:[1,0,1]
	v_pk_fma_f32 v[94:95], v[94:95], v[196:197], v[186:187] op_sel_hi:[1,0,1]
	v_cndmask_b32_e64 v97, v97, v245, s[14:15]
	v_cndmask_b32_e64 v95, v95, v245, s[14:15]
	v_cndmask_b32_e64 v94, v94, v245, s[14:15]
	v_cndmask_b32_e64 v96, v96, v245, s[14:15]
	v_cndmask_b32_e64 v103, v103, v245, s[14:15]
	v_cndmask_b32_e64 v102, v102, v245, s[14:15]
	v_cndmask_b32_e64 v105, v105, v245, s[14:15]
	v_cndmask_b32_e64 v104, v104, v245, s[14:15]
	s_and_b64 vcc, exec, s[18:19]
	v_lshl_add_u64 v[192:193], v[194:195], 2, s[60:61]
	s_cbranch_vccnz .LBB0_1383
	global_store_dwordx4 v[192:193], v[102:105], off
	global_store_dwordx4 v[192:193], v[94:97], off offset:16
	v_lshl_add_u64 v[190:191], v[194:195], 1, s[56:57]
	s_cbranch_execnz .LBB0_1282

.LBB0_1285:
	v_mov_b32_e32 v197, v196
	v_pk_mul_f32 v[112:113], v[112:113], v[140:141]
	v_pk_mul_f32 v[110:111], v[110:111], v[138:139]
	v_mov_b32_e32 v178, v196
	v_mov_b32_e32 v179, v196
	v_pk_mul_f32 v[108:109], v[108:109], v[136:137]
	v_pk_mul_f32 v[106:107], v[106:107], v[134:135]
	v_pk_fma_f32 v[112:113], v[112:113], v[178:179], v[188:189]
	v_pk_fma_f32 v[110:111], v[110:111], v[196:197], v[186:187]
	v_pk_fma_f32 v[108:109], v[108:109], v[178:179], v[184:185]
	v_pk_fma_f32 v[106:107], v[106:107], v[196:197], v[182:183]
	v_cndmask_b32_e64 v109, v109, v245, s[14:15]
	v_cndmask_b32_e64 v108, v108, v245, s[14:15]
	v_cndmask_b32_e64 v107, v107, v245, s[14:15]
	v_cndmask_b32_e64 v106, v106, v245, s[14:15]
	v_cndmask_b32_e64 v113, v113, v245, s[14:15]
	v_cndmask_b32_e64 v112, v112, v245, s[14:15]
	v_cndmask_b32_e64 v111, v111, v245, s[14:15]
	s_and_b64 vcc, exec, s[18:19]
	v_cndmask_b32_e64 v110, v110, v245, s[14:15]
	s_cbranch_vccnz .LBB0_1384
	global_store_dwordx4 v[192:193], v[110:113], off offset:512
	global_store_dwordx4 v[192:193], v[106:109], off offset:528
	s_cbranch_execnz .LBB0_1288

.LBB0_1288:
	ds_read_b32 v188, v235 offset:9216
	s_nop 0
	v_add_u32_e32 v178, 0x80, v228
	v_ashrrev_i32_e32 v179, 31, v178
	v_lshlrev_b64 v[186:187], 11, v[178:179]
	v_or_b32_e32 v186, v186, v239
	s_mov_b64 s[66:67], -1
	s_and_b64 vcc, exec, s[16:17]
	v_lshl_add_u64 v[190:191], v[186:187], 2, s[22:23]
	s_cbranch_vccnz .LBB0_1290
	global_load_dwordx4 v[178:181], v[190:191], off offset:16
	global_load_dwordx4 v[182:185], v[190:191], off
	s_waitcnt vmcnt(0)
	s_mov_b64 s[66:67], 0

.LBB0_1292:
	v_pk_mul_f32 v[128:129], v[128:129], v[152:153]
	v_pk_mul_f32 v[126:127], v[126:127], v[150:151]
	v_pk_mul_f32 v[120:121], v[120:121], v[148:149]
	v_pk_mul_f32 v[118:119], v[118:119], v[146:147]
	s_waitcnt lgkmcnt(0)
	v_pk_fma_f32 v[128:129], v[128:129], v[188:189], v[184:185] op_sel_hi:[1,0,1]
	v_pk_fma_f32 v[126:127], v[126:127], v[188:189], v[182:183] op_sel_hi:[1,0,1]
	v_pk_fma_f32 v[120:121], v[120:121], v[188:189], v[180:181] op_sel_hi:[1,0,1]
	v_pk_fma_f32 v[118:119], v[118:119], v[188:189], v[178:179] op_sel_hi:[1,0,1]
	v_cndmask_b32_e64 v121, v121, v245, s[14:15]
	v_cndmask_b32_e64 v119, v119, v245, s[14:15]
	v_cndmask_b32_e64 v118, v118, v245, s[14:15]
	v_cndmask_b32_e64 v120, v120, v245, s[14:15]
	v_cndmask_b32_e64 v127, v127, v245, s[14:15]
	v_cndmask_b32_e64 v126, v126, v245, s[14:15]
	v_cndmask_b32_e64 v129, v129, v245, s[14:15]
	v_cndmask_b32_e64 v128, v128, v245, s[14:15]
	s_and_b64 vcc, exec, s[18:19]
	v_lshl_add_u64 v[184:185], v[186:187], 2, s[60:61]
	s_cbranch_vccnz .LBB0_1385
	global_store_dwordx4 v[184:185], v[126:129], off
	global_store_dwordx4 v[184:185], v[118:121], off offset:16
	v_lshl_add_u64 v[182:183], v[186:187], 1, s[56:57]
	s_cbranch_execnz .LBB0_1295

.LBB0_1298:
	v_mov_b32_e32 v189, v188
	v_pk_mul_f32 v[124:125], v[124:125], v[140:141]
	v_pk_mul_f32 v[122:123], v[122:123], v[138:139]
	v_mov_b32_e32 v170, v188
	v_mov_b32_e32 v171, v188
	v_pk_mul_f32 v[116:117], v[116:117], v[136:137]
	v_pk_mul_f32 v[114:115], v[114:115], v[134:135]
	v_pk_fma_f32 v[124:125], v[124:125], v[170:171], v[180:181]
	v_pk_fma_f32 v[122:123], v[122:123], v[188:189], v[178:179]
	v_pk_fma_f32 v[116:117], v[116:117], v[170:171], v[176:177]
	v_pk_fma_f32 v[114:115], v[114:115], v[188:189], v[174:175]
	v_cndmask_b32_e64 v117, v117, v245, s[14:15]
	v_cndmask_b32_e64 v116, v116, v245, s[14:15]
	v_cndmask_b32_e64 v115, v115, v245, s[14:15]
	v_cndmask_b32_e64 v114, v114, v245, s[14:15]
	v_cndmask_b32_e64 v125, v125, v245, s[14:15]
	v_cndmask_b32_e64 v124, v124, v245, s[14:15]
	v_cndmask_b32_e64 v123, v123, v245, s[14:15]
	s_and_b64 vcc, exec, s[18:19]
	v_cndmask_b32_e64 v122, v122, v245, s[14:15]
	s_cbranch_vccnz .LBB0_1386
	global_store_dwordx4 v[184:185], v[122:125], off offset:512
	global_store_dwordx4 v[184:185], v[114:117], off offset:528
	s_cbranch_execnz .LBB0_1301

.LBB0_1301:
	ds_read_b32 v180, v235 offset:9344
	s_nop 0
	v_add_u32_e32 v170, 0x90, v228
	v_ashrrev_i32_e32 v171, 31, v170
	v_lshlrev_b64 v[178:179], 11, v[170:171]
	v_or_b32_e32 v178, v178, v239
	s_mov_b64 s[66:67], -1
	s_and_b64 vcc, exec, s[16:17]
	v_lshl_add_u64 v[182:183], v[178:179], 2, s[22:23]
	s_cbranch_vccnz .LBB0_1303
	global_load_dwordx4 v[170:173], v[182:183], off offset:16
	global_load_dwordx4 v[174:177], v[182:183], off
	s_waitcnt vmcnt(0)
	s_mov_b64 s[66:67], 0

.LBB0_1305:
	v_pk_mul_f32 v[100:101], v[100:101], v[152:153]
	v_pk_mul_f32 v[98:99], v[98:99], v[150:151]
	v_pk_mul_f32 v[92:93], v[92:93], v[148:149]
	v_pk_mul_f32 v[90:91], v[90:91], v[146:147]
	s_waitcnt lgkmcnt(0)
	v_pk_fma_f32 v[100:101], v[100:101], v[180:181], v[176:177] op_sel_hi:[1,0,1]
	v_pk_fma_f32 v[98:99], v[98:99], v[180:181], v[174:175] op_sel_hi:[1,0,1]
	v_pk_fma_f32 v[92:93], v[92:93], v[180:181], v[172:173] op_sel_hi:[1,0,1]
	v_pk_fma_f32 v[90:91], v[90:91], v[180:181], v[170:171] op_sel_hi:[1,0,1]
	v_cndmask_b32_e64 v93, v93, v245, s[14:15]
	v_cndmask_b32_e64 v91, v91, v245, s[14:15]
	v_cndmask_b32_e64 v90, v90, v245, s[14:15]
	v_cndmask_b32_e64 v92, v92, v245, s[14:15]
	v_cndmask_b32_e64 v99, v99, v245, s[14:15]
	v_cndmask_b32_e64 v98, v98, v245, s[14:15]
	v_cndmask_b32_e64 v101, v101, v245, s[14:15]
	v_cndmask_b32_e64 v100, v100, v245, s[14:15]
	s_and_b64 vcc, exec, s[18:19]
	v_lshl_add_u64 v[176:177], v[178:179], 2, s[60:61]
	s_cbranch_vccnz .LBB0_1387
	global_store_dwordx4 v[176:177], v[98:101], off
	global_store_dwordx4 v[176:177], v[90:93], off offset:16
	v_lshl_add_u64 v[174:175], v[178:179], 1, s[56:57]
	s_cbranch_execnz .LBB0_1308

.LBB0_1311:
	v_mov_b32_e32 v181, v180
	v_pk_mul_f32 v[72:73], v[72:73], v[140:141]
	v_pk_mul_f32 v[70:71], v[70:71], v[138:139]
	v_mov_b32_e32 v162, v180
	v_mov_b32_e32 v163, v180
	v_pk_mul_f32 v[64:65], v[64:65], v[136:137]
	v_pk_mul_f32 v[62:63], v[62:63], v[134:135]
	v_pk_fma_f32 v[72:73], v[72:73], v[162:163], v[172:173]
	v_pk_fma_f32 v[70:71], v[70:71], v[180:181], v[170:171]
	v_pk_fma_f32 v[64:65], v[64:65], v[162:163], v[168:169]
	v_pk_fma_f32 v[62:63], v[62:63], v[180:181], v[166:167]
	v_cndmask_b32_e64 v65, v65, v245, s[14:15]
	v_cndmask_b32_e64 v64, v64, v245, s[14:15]
	v_cndmask_b32_e64 v63, v63, v245, s[14:15]
	v_cndmask_b32_e64 v62, v62, v245, s[14:15]
	v_cndmask_b32_e64 v73, v73, v245, s[14:15]
	v_cndmask_b32_e64 v72, v72, v245, s[14:15]
	v_cndmask_b32_e64 v71, v71, v245, s[14:15]
	s_and_b64 vcc, exec, s[18:19]
	v_cndmask_b32_e64 v70, v70, v245, s[14:15]
	s_cbranch_vccnz .LBB0_1388
	global_store_dwordx4 v[176:177], v[70:73], off offset:512
	global_store_dwordx4 v[176:177], v[62:65], off offset:528
	s_cbranch_execnz .LBB0_1314

.LBB0_1314:
	ds_read_b32 v172, v235 offset:9472
	s_nop 0
	v_add_u32_e32 v162, 0xa0, v228
	v_ashrrev_i32_e32 v163, 31, v162
	v_lshlrev_b64 v[170:171], 11, v[162:163]
	v_or_b32_e32 v170, v170, v239
	s_mov_b64 s[66:67], -1
	s_and_b64 vcc, exec, s[16:17]
	v_lshl_add_u64 v[174:175], v[170:171], 2, s[22:23]
	s_cbranch_vccnz .LBB0_1316
	global_load_dwordx4 v[162:165], v[174:175], off offset:16
	global_load_dwordx4 v[166:169], v[174:175], off
	s_waitcnt vmcnt(0)
	s_mov_b64 s[66:67], 0

.LBB0_1318:
	v_pk_mul_f32 v[48:49], v[48:49], v[152:153]
	v_pk_mul_f32 v[46:47], v[46:47], v[150:151]
	v_pk_mul_f32 v[40:41], v[40:41], v[148:149]
	v_pk_mul_f32 v[38:39], v[38:39], v[146:147]
	s_waitcnt lgkmcnt(0)
	v_pk_fma_f32 v[48:49], v[48:49], v[172:173], v[168:169] op_sel_hi:[1,0,1]
	v_pk_fma_f32 v[46:47], v[46:47], v[172:173], v[166:167] op_sel_hi:[1,0,1]
	v_pk_fma_f32 v[40:41], v[40:41], v[172:173], v[164:165] op_sel_hi:[1,0,1]
	v_pk_fma_f32 v[38:39], v[38:39], v[172:173], v[162:163] op_sel_hi:[1,0,1]
	v_cndmask_b32_e64 v41, v41, v245, s[14:15]
	v_cndmask_b32_e64 v39, v39, v245, s[14:15]
	v_cndmask_b32_e64 v38, v38, v245, s[14:15]
	v_cndmask_b32_e64 v40, v40, v245, s[14:15]
	v_cndmask_b32_e64 v47, v47, v245, s[14:15]
	v_cndmask_b32_e64 v46, v46, v245, s[14:15]
	v_cndmask_b32_e64 v49, v49, v245, s[14:15]
	v_cndmask_b32_e64 v48, v48, v245, s[14:15]
	s_and_b64 vcc, exec, s[18:19]
	v_lshl_add_u64 v[168:169], v[170:171], 2, s[60:61]
	s_cbranch_vccnz .LBB0_1389
	global_store_dwordx4 v[168:169], v[46:49], off
	global_store_dwordx4 v[168:169], v[38:41], off offset:16
	v_lshl_add_u64 v[166:167], v[170:171], 1, s[56:57]
	s_cbranch_execnz .LBB0_1321

.LBB0_1324:
	v_mov_b32_e32 v173, v172
	v_pk_mul_f32 v[24:25], v[24:25], v[140:141]
	v_pk_mul_f32 v[22:23], v[22:23], v[138:139]
	v_mov_b32_e32 v154, v172
	v_mov_b32_e32 v155, v172
	v_pk_mul_f32 v[20:21], v[20:21], v[136:137]
	v_pk_mul_f32 v[18:19], v[18:19], v[134:135]
	v_pk_fma_f32 v[24:25], v[24:25], v[154:155], v[164:165]
	v_pk_fma_f32 v[22:23], v[22:23], v[172:173], v[162:163]
	v_pk_fma_f32 v[20:21], v[20:21], v[154:155], v[160:161]
	v_pk_fma_f32 v[18:19], v[18:19], v[172:173], v[158:159]
	v_cndmask_b32_e64 v21, v21, v245, s[14:15]
	v_cndmask_b32_e64 v20, v20, v245, s[14:15]
	v_cndmask_b32_e64 v19, v19, v245, s[14:15]
	v_cndmask_b32_e64 v18, v18, v245, s[14:15]
	v_cndmask_b32_e64 v25, v25, v245, s[14:15]
	v_cndmask_b32_e64 v24, v24, v245, s[14:15]
	v_cndmask_b32_e64 v23, v23, v245, s[14:15]
	s_and_b64 vcc, exec, s[18:19]
	v_cndmask_b32_e64 v22, v22, v245, s[14:15]
	s_cbranch_vccnz .LBB0_1390
	global_store_dwordx4 v[168:169], v[22:25], off offset:512
	global_store_dwordx4 v[168:169], v[18:21], off offset:528
	s_cbranch_execnz .LBB0_1327

.LBB0_1327:
	ds_read_b32 v164, v235 offset:9600
	s_nop 0
	v_add_u32_e32 v154, 0xb0, v228
	v_ashrrev_i32_e32 v155, 31, v154
	v_lshlrev_b64 v[162:163], 11, v[154:155]
	v_or_b32_e32 v162, v162, v239
	s_mov_b64 s[66:67], -1
	s_and_b64 vcc, exec, s[16:17]
	v_lshl_add_u64 v[166:167], v[162:163], 2, s[22:23]
	s_cbranch_vccnz .LBB0_1329
	global_load_dwordx4 v[154:157], v[166:167], off offset:16
	global_load_dwordx4 v[158:161], v[166:167], off
	s_waitcnt vmcnt(0)
	s_mov_b64 s[66:67], 0

.LBB0_1331:
	v_pk_mul_f32 v[16:17], v[16:17], v[152:153]
	v_pk_mul_f32 v[14:15], v[14:15], v[150:151]
	v_pk_mul_f32 v[12:13], v[12:13], v[148:149]
	v_pk_mul_f32 v[10:11], v[10:11], v[146:147]
	s_waitcnt lgkmcnt(0)
	v_pk_fma_f32 v[16:17], v[16:17], v[164:165], v[160:161] op_sel_hi:[1,0,1]
	v_pk_fma_f32 v[14:15], v[14:15], v[164:165], v[158:159] op_sel_hi:[1,0,1]
	v_pk_fma_f32 v[12:13], v[12:13], v[164:165], v[156:157] op_sel_hi:[1,0,1]
	v_pk_fma_f32 v[10:11], v[10:11], v[164:165], v[154:155] op_sel_hi:[1,0,1]
	v_cndmask_b32_e64 v13, v13, v245, s[14:15]
	v_cndmask_b32_e64 v11, v11, v245, s[14:15]
	v_cndmask_b32_e64 v10, v10, v245, s[14:15]
	v_cndmask_b32_e64 v12, v12, v245, s[14:15]
	v_cndmask_b32_e64 v15, v15, v245, s[14:15]
	v_cndmask_b32_e64 v14, v14, v245, s[14:15]
	v_cndmask_b32_e64 v17, v17, v245, s[14:15]
	v_cndmask_b32_e64 v16, v16, v245, s[14:15]
	s_and_b64 vcc, exec, s[18:19]
	v_lshl_add_u64 v[152:153], v[162:163], 2, s[60:61]
	s_cbranch_vccnz .LBB0_1391
	global_store_dwordx4 v[152:153], v[14:17], off
	global_store_dwordx4 v[152:153], v[10:13], off offset:16
	v_lshl_add_u64 v[150:151], v[162:163], 1, s[56:57]
	s_cbranch_execnz .LBB0_1334

.LBB0_1337:
	v_mov_b32_e32 v165, v164
	v_pk_mul_f32 v[8:9], v[8:9], v[140:141]
	v_pk_mul_f32 v[6:7], v[6:7], v[138:139]
	v_mov_b32_e32 v130, v164
	v_mov_b32_e32 v131, v164
	v_pk_mul_f32 v[4:5], v[4:5], v[136:137]
	v_pk_mul_f32 v[2:3], v[2:3], v[134:135]
	v_pk_fma_f32 v[8:9], v[8:9], v[130:131], v[148:149]
	v_pk_fma_f32 v[6:7], v[6:7], v[164:165], v[146:147]
	v_pk_fma_f32 v[4:5], v[4:5], v[130:131], v[144:145]
	v_pk_fma_f32 v[2:3], v[2:3], v[164:165], v[142:143]
	v_cndmask_b32_e64 v5, v5, v245, s[14:15]
	v_cndmask_b32_e64 v4, v4, v245, s[14:15]
	v_cndmask_b32_e64 v3, v3, v245, s[14:15]
	v_cndmask_b32_e64 v2, v2, v245, s[14:15]
	v_cndmask_b32_e64 v9, v9, v245, s[14:15]
	v_cndmask_b32_e64 v8, v8, v245, s[14:15]
	v_cndmask_b32_e64 v7, v7, v245, s[14:15]
	s_and_b64 vcc, exec, s[18:19]
	v_cndmask_b32_e64 v6, v6, v245, s[14:15]
	s_cbranch_vccnz .LBB0_1392
	global_store_dwordx4 v[152:153], v[6:9], off offset:512
	global_store_dwordx4 v[152:153], v[2:5], off offset:528
	s_cbranch_execnz .LBB0_1340
